# v077 with 6 more LDS-DMA loads converted to the saddr form (zero-extension proof searched further back)
# baseline (speedup 1.0000x reference)
.LBB0_1746:
	ds_read_b128 v[128:131], v237
	ds_read_b128 v[132:135], v237 offset:1024
	ds_read_b128 v[136:139], v237 offset:2048
	ds_read_b128 v[140:143], v237 offset:3072
	s_add_u32 s26, s16, 0xfff80080
	s_addc_u32 s27, s17, -1
	s_cmp_eq_u32 s29, 28
	s_cselect_b32 s35, s43, s27
	s_cselect_b32 s34, s42, s26
	s_cselect_b32 s27, s45, s11
	s_cselect_b32 s26, s44, s10
	s_mov_b32 m0, s14
	ds_read_b128 v[148:151], v236
	ds_read_b128 v[152:155], v236 offset:1024
	ds_read_b128 v[156:159], v236 offset:2048
	ds_read_b128 v[160:163], v236 offset:3072
	ds_read_b128 v[164:167], v236 offset:4096
	ds_read_b128 v[168:171], v236 offset:5120
	ds_read_b128 v[172:175], v236 offset:6144
	ds_read_b128 v[176:179], v236 offset:7168
	global_load_lds_dwordx4 v210, s[16:17]
	s_mov_b32 m0, s15
	s_nop 0
	global_load_lds_dwordx4 v214, s[16:17]
	s_barrier
	s_waitcnt lgkmcnt(0)
	v_mfma_f32_16x16x32_f16 v[80:83], v[128:131], v[148:151], v[80:83]
	v_mfma_f32_16x16x32_f16 v[108:111], v[136:139], v[148:151], v[108:111]
	v_mfma_f32_16x16x32_f16 v[56:59], v[128:131], v[156:159], v[56:59]
	v_mfma_f32_16x16x32_f16 v[68:71], v[136:139], v[156:159], v[68:71]
	v_mfma_f32_16x16x32_f16 v[28:31], v[128:131], v[164:167], v[28:31]
	v_mfma_f32_16x16x32_f16 v[36:39], v[136:139], v[164:167], v[36:39]
	v_mfma_f32_16x16x32_f16 v[16:19], v[128:131], v[172:175], v[16:19]
	v_mfma_f32_16x16x32_f16 v[12:15], v[136:139], v[172:175], v[12:15]
	v_mfma_f32_16x16x32_f16 v[80:83], v[132:135], v[152:155], v[80:83]
	v_mfma_f32_16x16x32_f16 v[108:111], v[140:143], v[152:155], v[108:111]
	v_mfma_f32_16x16x32_f16 v[56:59], v[132:135], v[160:163], v[56:59]
	v_mfma_f32_16x16x32_f16 v[68:71], v[140:143], v[160:163], v[68:71]
	v_mfma_f32_16x16x32_f16 v[28:31], v[132:135], v[168:171], v[28:31]
	v_mfma_f32_16x16x32_f16 v[36:39], v[140:143], v[168:171], v[36:39]
	v_mfma_f32_16x16x32_f16 v[16:19], v[132:135], v[176:179], v[16:19]
	v_mfma_f32_16x16x32_f16 v[12:15], v[140:143], v[176:179], v[12:15]
	s_barrier
	s_mov_b32 m0, s19
	v_lshl_add_u64 v[196:197], s[26:27], 0, v[2:3]
	ds_read_b128 v[180:183], v238
	ds_read_b128 v[184:187], v238 offset:1024
	ds_read_b128 v[188:191], v238 offset:2048
	ds_read_b128 v[192:195], v238 offset:3072
	global_load_lds_dwordx4 v[196:197], off
	v_lshl_add_u64 v[198:199], s[26:27], 0, v[206:207]
	s_mov_b32 m0, s37
	s_nop 0
	global_load_lds_dwordx4 v[198:199], off
	s_waitcnt vmcnt(10)
	s_barrier
	s_waitcnt lgkmcnt(0)
	v_mfma_f32_16x16x32_f16 v[72:75], v[180:183], v[148:151], v[72:75]
	v_mfma_f32_16x16x32_f16 v[88:91], v[188:191], v[148:151], v[88:91]
	v_mfma_f32_16x16x32_f16 v[40:43], v[180:183], v[156:159], v[40:43]
	v_mfma_f32_16x16x32_f16 v[52:55], v[188:191], v[156:159], v[52:55]
	v_mfma_f32_16x16x32_f16 v[20:23], v[180:183], v[164:167], v[20:23]
	v_mfma_f32_16x16x32_f16 v[24:27], v[188:191], v[164:167], v[24:27]
	v_mfma_f32_16x16x32_f16 v[8:11], v[180:183], v[172:175], v[8:11]
	v_mfma_f32_16x16x32_f16 v[4:7], v[188:191], v[172:175], v[4:7]
	v_mfma_f32_16x16x32_f16 v[72:75], v[184:187], v[152:155], v[72:75]
	v_mfma_f32_16x16x32_f16 v[88:91], v[192:195], v[152:155], v[88:91]
	v_mfma_f32_16x16x32_f16 v[40:43], v[184:187], v[160:163], v[40:43]
	v_mfma_f32_16x16x32_f16 v[52:55], v[192:195], v[160:163], v[52:55]
	v_mfma_f32_16x16x32_f16 v[20:23], v[184:187], v[168:171], v[20:23]
	v_mfma_f32_16x16x32_f16 v[24:27], v[192:195], v[168:171], v[24:27]
	v_mfma_f32_16x16x32_f16 v[8:11], v[184:187], v[176:179], v[8:11]
	v_mfma_f32_16x16x32_f16 v[4:7], v[192:195], v[176:179], v[4:7]
	s_mov_b32 m0, s7
	v_lshl_add_u64 v[200:201], s[34:35], 0, v[210:211]
	s_barrier
	ds_read_b128 v[148:151], v236 offset:16384
	ds_read_b128 v[152:155], v236 offset:17408
	ds_read_b128 v[156:159], v236 offset:18432
	ds_read_b128 v[160:163], v236 offset:19456
	ds_read_b128 v[164:167], v236 offset:20480
	ds_read_b128 v[168:171], v236 offset:21504
	ds_read_b128 v[172:175], v236 offset:22528
	ds_read_b128 v[176:179], v236 offset:23552
	global_load_lds_dwordx4 v[200:201], off
	v_lshl_add_u64 v[202:203], s[34:35], 0, v[208:209]
	s_mov_b32 m0, s8
	s_nop 0
	global_load_lds_dwordx4 v[202:203], off
	s_barrier
	s_waitcnt lgkmcnt(0)
	v_mfma_f32_16x16x32_f16 v[124:127], v[128:131], v[148:151], v[124:127]
	v_mfma_f32_16x16x32_f16 v[144:147], v[136:139], v[148:151], v[144:147]
	v_mfma_f32_16x16x32_f16 v[104:107], v[128:131], v[156:159], v[104:107]
	v_mfma_f32_16x16x32_f16 v[112:115], v[136:139], v[156:159], v[112:115]
	v_mfma_f32_16x16x32_f16 v[84:87], v[128:131], v[164:167], v[84:87]
	v_mfma_f32_16x16x32_f16 v[92:95], v[136:139], v[164:167], v[92:95]
	v_mfma_f32_16x16x32_f16 v[48:51], v[128:131], v[172:175], v[48:51]
	v_mfma_f32_16x16x32_f16 v[60:63], v[136:139], v[172:175], v[60:63]
	v_mfma_f32_16x16x32_f16 v[124:127], v[132:135], v[152:155], v[124:127]
	v_mfma_f32_16x16x32_f16 v[144:147], v[140:143], v[152:155], v[144:147]
	v_mfma_f32_16x16x32_f16 v[104:107], v[132:135], v[160:163], v[104:107]
	v_mfma_f32_16x16x32_f16 v[112:115], v[140:143], v[160:163], v[112:115]
	v_mfma_f32_16x16x32_f16 v[84:87], v[132:135], v[168:171], v[84:87]
	v_mfma_f32_16x16x32_f16 v[92:95], v[140:143], v[168:171], v[92:95]
	v_mfma_f32_16x16x32_f16 v[48:51], v[132:135], v[176:179], v[48:51]
	v_mfma_f32_16x16x32_f16 v[60:63], v[140:143], v[176:179], v[60:63]
	s_barrier
	s_add_u32 s30, s26, 0x80000
	s_addc_u32 s31, s27, 0
	s_mov_b32 m0, s63
	v_lshl_add_u64 v[128:129], s[30:31], 0, v[2:3]
	global_load_lds_dwordx4 v[128:129], off
	s_mov_b32 m0, s68
	s_nop 0
	global_load_lds_dwordx4 v206, s[30:31]
	s_waitcnt vmcnt(8)
	s_barrier
	v_mfma_f32_16x16x32_f16 v[116:119], v[180:183], v[148:151], v[116:119]
	v_mfma_f32_16x16x32_f16 v[120:123], v[188:191], v[148:151], v[120:123]
	v_mfma_f32_16x16x32_f16 v[96:99], v[180:183], v[156:159], v[96:99]
	v_mfma_f32_16x16x32_f16 v[100:103], v[188:191], v[156:159], v[100:103]
	v_mfma_f32_16x16x32_f16 v[64:67], v[180:183], v[164:167], v[64:67]
	v_mfma_f32_16x16x32_f16 v[76:79], v[188:191], v[164:167], v[76:79]
	v_mfma_f32_16x16x32_f16 v[32:35], v[180:183], v[172:175], v[32:35]
	v_mfma_f32_16x16x32_f16 v[44:47], v[188:191], v[172:175], v[44:47]
	v_mfma_f32_16x16x32_f16 v[116:119], v[184:187], v[152:155], v[116:119]
	v_mfma_f32_16x16x32_f16 v[120:123], v[192:195], v[152:155], v[120:123]
	v_mfma_f32_16x16x32_f16 v[96:99], v[184:187], v[160:163], v[96:99]
	v_mfma_f32_16x16x32_f16 v[100:103], v[192:195], v[160:163], v[100:103]
	v_mfma_f32_16x16x32_f16 v[64:67], v[184:187], v[168:171], v[64:67]
	v_mfma_f32_16x16x32_f16 v[76:79], v[192:195], v[168:171], v[76:79]
	v_mfma_f32_16x16x32_f16 v[32:35], v[184:187], v[176:179], v[32:35]
	v_mfma_f32_16x16x32_f16 v[44:47], v[192:195], v[176:179], v[44:47]
	s_barrier
	ds_read_b128 v[128:131], v239
	ds_read_b128 v[132:135], v239 offset:1024
	ds_read_b128 v[136:139], v239 offset:2048
	ds_read_b128 v[140:143], v239 offset:3072
	s_add_u32 s30, s34, 0x80000
	s_addc_u32 s31, s35, 0
	s_mov_b32 m0, s9
	ds_read_b128 v[148:151], v236 offset:32768
	ds_read_b128 v[152:155], v236 offset:33792
	ds_read_b128 v[156:159], v236 offset:34816
	ds_read_b128 v[160:163], v236 offset:35840
	ds_read_b128 v[164:167], v236 offset:36864
	ds_read_b128 v[168:171], v236 offset:37888
	ds_read_b128 v[172:175], v236 offset:38912
	ds_read_b128 v[176:179], v236 offset:39936
	global_load_lds_dwordx4 v210, s[30:31]
	s_mov_b32 m0, s12
	s_nop 0
	global_load_lds_dwordx4 v208, s[30:31]
	s_barrier
	s_waitcnt lgkmcnt(0)
	v_mfma_f32_16x16x32_f16 v[80:83], v[128:131], v[148:151], v[80:83]
	v_mfma_f32_16x16x32_f16 v[108:111], v[136:139], v[148:151], v[108:111]
	v_mfma_f32_16x16x32_f16 v[56:59], v[128:131], v[156:159], v[56:59]
	v_mfma_f32_16x16x32_f16 v[68:71], v[136:139], v[156:159], v[68:71]
	v_mfma_f32_16x16x32_f16 v[28:31], v[128:131], v[164:167], v[28:31]
	v_mfma_f32_16x16x32_f16 v[36:39], v[136:139], v[164:167], v[36:39]
	v_mfma_f32_16x16x32_f16 v[16:19], v[128:131], v[172:175], v[16:19]
	v_mfma_f32_16x16x32_f16 v[12:15], v[136:139], v[172:175], v[12:15]
	v_mfma_f32_16x16x32_f16 v[80:83], v[132:135], v[152:155], v[80:83]
	v_mfma_f32_16x16x32_f16 v[108:111], v[140:143], v[152:155], v[108:111]
	v_mfma_f32_16x16x32_f16 v[56:59], v[132:135], v[160:163], v[56:59]
	v_mfma_f32_16x16x32_f16 v[68:71], v[140:143], v[160:163], v[68:71]
	v_mfma_f32_16x16x32_f16 v[28:31], v[132:135], v[168:171], v[28:31]
	v_mfma_f32_16x16x32_f16 v[36:39], v[140:143], v[168:171], v[36:39]
	v_mfma_f32_16x16x32_f16 v[16:19], v[132:135], v[176:179], v[16:19]
	v_mfma_f32_16x16x32_f16 v[12:15], v[140:143], v[176:179], v[12:15]
	s_barrier
	s_mov_b32 m0, s69
	v_lshl_add_u64 v[196:197], v[196:197], 0, s[88:89]
	ds_read_b128 v[180:183], v240
	ds_read_b128 v[184:187], v240 offset:1024
	ds_read_b128 v[188:191], v240 offset:2048
	ds_read_b128 v[192:195], v240 offset:3072
	global_load_lds_dwordx4 v[196:197], off
	v_lshl_add_u64 v[196:197], v[198:199], 0, s[88:89]
	s_mov_b32 m0, s70
	s_nop 0
	global_load_lds_dwordx4 v[196:197], off
	s_waitcnt vmcnt(10)
	s_barrier
	s_waitcnt lgkmcnt(0)
	v_mfma_f32_16x16x32_f16 v[72:75], v[180:183], v[148:151], v[72:75]
	v_mfma_f32_16x16x32_f16 v[88:91], v[188:191], v[148:151], v[88:91]
	v_mfma_f32_16x16x32_f16 v[40:43], v[180:183], v[156:159], v[40:43]
	v_mfma_f32_16x16x32_f16 v[52:55], v[188:191], v[156:159], v[52:55]
	v_mfma_f32_16x16x32_f16 v[20:23], v[180:183], v[164:167], v[20:23]
	v_mfma_f32_16x16x32_f16 v[24:27], v[188:191], v[164:167], v[24:27]
	v_mfma_f32_16x16x32_f16 v[8:11], v[180:183], v[172:175], v[8:11]
	v_mfma_f32_16x16x32_f16 v[4:7], v[188:191], v[172:175], v[4:7]
	v_mfma_f32_16x16x32_f16 v[72:75], v[184:187], v[152:155], v[72:75]
	v_mfma_f32_16x16x32_f16 v[88:91], v[192:195], v[152:155], v[88:91]
	v_mfma_f32_16x16x32_f16 v[40:43], v[184:187], v[160:163], v[40:43]
	v_mfma_f32_16x16x32_f16 v[52:55], v[192:195], v[160:163], v[52:55]
	v_mfma_f32_16x16x32_f16 v[20:23], v[184:187], v[168:171], v[20:23]
	v_mfma_f32_16x16x32_f16 v[24:27], v[192:195], v[168:171], v[24:27]
	v_mfma_f32_16x16x32_f16 v[8:11], v[184:187], v[176:179], v[8:11]
	v_mfma_f32_16x16x32_f16 v[4:7], v[192:195], v[176:179], v[4:7]
	s_mov_b32 m0, s39
	v_lshl_add_u64 v[196:197], v[200:201], 0, s[88:89]
	s_barrier
	ds_read_b128 v[148:151], v236 offset:49152
	ds_read_b128 v[152:155], v236 offset:50176
	ds_read_b128 v[156:159], v236 offset:51200
	ds_read_b128 v[160:163], v236 offset:52224
	ds_read_b128 v[164:167], v236 offset:53248
	ds_read_b128 v[168:171], v236 offset:54272
	ds_read_b128 v[172:175], v236 offset:55296
	ds_read_b128 v[176:179], v236 offset:56320
	global_load_lds_dwordx4 v[196:197], off
	v_lshl_add_u64 v[196:197], v[202:203], 0, s[88:89]
	s_mov_b32 m0, s47
	s_nop 0
	global_load_lds_dwordx4 v[196:197], off
	s_barrier
	s_waitcnt lgkmcnt(0)
	v_mfma_f32_16x16x32_f16 v[124:127], v[128:131], v[148:151], v[124:127]
	v_mfma_f32_16x16x32_f16 v[144:147], v[136:139], v[148:151], v[144:147]
	v_mfma_f32_16x16x32_f16 v[104:107], v[128:131], v[156:159], v[104:107]
	v_mfma_f32_16x16x32_f16 v[112:115], v[136:139], v[156:159], v[112:115]
	v_mfma_f32_16x16x32_f16 v[84:87], v[128:131], v[164:167], v[84:87]
	v_mfma_f32_16x16x32_f16 v[92:95], v[136:139], v[164:167], v[92:95]
	v_mfma_f32_16x16x32_f16 v[48:51], v[128:131], v[172:175], v[48:51]
	v_mfma_f32_16x16x32_f16 v[60:63], v[136:139], v[172:175], v[60:63]
	v_mfma_f32_16x16x32_f16 v[124:127], v[132:135], v[152:155], v[124:127]
	v_mfma_f32_16x16x32_f16 v[144:147], v[140:143], v[152:155], v[144:147]
	v_mfma_f32_16x16x32_f16 v[104:107], v[132:135], v[160:163], v[104:107]
	v_mfma_f32_16x16x32_f16 v[112:115], v[140:143], v[160:163], v[112:115]
	v_mfma_f32_16x16x32_f16 v[84:87], v[132:135], v[168:171], v[84:87]
	v_mfma_f32_16x16x32_f16 v[92:95], v[140:143], v[168:171], v[92:95]
	v_mfma_f32_16x16x32_f16 v[48:51], v[132:135], v[176:179], v[48:51]
	v_mfma_f32_16x16x32_f16 v[60:63], v[140:143], v[176:179], v[60:63]
	s_barrier
	s_add_u32 s26, s26, 0x80080
	s_addc_u32 s27, s27, 0
	s_mov_b32 m0, s71
	v_lshl_add_u64 v[128:129], s[26:27], 0, v[2:3]
	global_load_lds_dwordx4 v[128:129], off
	s_mov_b32 m0, s76
	s_nop 0
	global_load_lds_dwordx4 v206, s[26:27]
	s_waitcnt vmcnt(8)
	s_barrier
	v_mfma_f32_16x16x32_f16 v[116:119], v[180:183], v[148:151], v[116:119]
	v_mfma_f32_16x16x32_f16 v[120:123], v[188:191], v[148:151], v[120:123]
	v_mfma_f32_16x16x32_f16 v[96:99], v[180:183], v[156:159], v[96:99]
	v_mfma_f32_16x16x32_f16 v[100:103], v[188:191], v[156:159], v[100:103]
	v_mfma_f32_16x16x32_f16 v[64:67], v[180:183], v[164:167], v[64:67]
	v_mfma_f32_16x16x32_f16 v[76:79], v[188:191], v[164:167], v[76:79]
	v_mfma_f32_16x16x32_f16 v[32:35], v[180:183], v[172:175], v[32:35]
	v_mfma_f32_16x16x32_f16 v[44:47], v[188:191], v[172:175], v[44:47]
	v_mfma_f32_16x16x32_f16 v[116:119], v[184:187], v[152:155], v[116:119]
	v_mfma_f32_16x16x32_f16 v[120:123], v[192:195], v[152:155], v[120:123]
	v_mfma_f32_16x16x32_f16 v[96:99], v[184:187], v[160:163], v[96:99]
	v_mfma_f32_16x16x32_f16 v[100:103], v[192:195], v[160:163], v[100:103]
	v_mfma_f32_16x16x32_f16 v[64:67], v[184:187], v[168:171], v[64:67]
	v_mfma_f32_16x16x32_f16 v[76:79], v[192:195], v[168:171], v[76:79]
	v_mfma_f32_16x16x32_f16 v[32:35], v[184:187], v[176:179], v[32:35]
	v_mfma_f32_16x16x32_f16 v[44:47], v[192:195], v[176:179], v[44:47]
	s_add_i32 s29, s29, 2
	s_add_u32 s16, s16, 0x100
	s_addc_u32 s17, s17, 0
	s_add_u32 s10, s10, 0x100
	s_addc_u32 s11, s11, 0
	s_cmp_lt_u32 s29, 30
	s_barrier
	s_cbranch_scc1 .LBB0_1746
	s_add_i32 s10, s46, 16
	s_mul_hi_i32 s11, s10, 0x42
	s_mulk_i32 s10, 0x42
	s_add_u32 s10, s10, s48
	v_mov_b32_e32 v128, v233
	s_addc_u32 s11, s11, s78
	v_mov_b32_e32 v129, v234
	s_lshl_b64 s[10:11], s[10:11], 17
	v_add_u32_e32 v202, s13, v128
	v_lshlrev_b32_e32 v128, 8, v202
	v_lshlrev_b32_e32 v196, 3, v129
	s_add_u32 s10, s4, s10
	s_addc_u32 s11, s6, s11
	v_ashrrev_i32_e32 v197, 31, v196
	v_add_u32_e32 v140, 0x8000, v128
	v_lshl_add_u64 v[130:131], v[196:197], 1, s[10:11]
	v_ashrrev_i32_e32 v141, 31, v140
	v_lshl_add_u64 v[160:161], v[140:141], 1, v[130:131]
	v_add_u32_e32 v140, 0x9000, v128
	v_ashrrev_i32_e32 v129, 31, v128
	v_ashrrev_i32_e32 v141, 31, v140
	v_lshl_add_u64 v[132:133], v[128:129], 1, v[130:131]
	v_add_u32_e32 v134, 0x1000, v128
	v_add_u32_e32 v136, 0x2000, v128
	v_add_u32_e32 v138, 0x3000, v128
	v_lshl_add_u64 v[152:153], v[140:141], 1, v[130:131]
	v_add_u32_e32 v140, 0xa000, v128
	v_add_u32_e32 v128, 0xb000, v128
	v_ashrrev_i32_e32 v135, 31, v134
	v_ashrrev_i32_e32 v137, 31, v136
	v_ashrrev_i32_e32 v139, 31, v138
	v_ashrrev_i32_e32 v141, 31, v140
	v_ashrrev_i32_e32 v129, 31, v128
	v_lshl_add_u64 v[134:135], v[134:135], 1, v[130:131]
	v_lshl_add_u64 v[136:137], v[136:137], 1, v[130:131]
	v_lshl_add_u64 v[138:139], v[138:139], 1, v[130:131]
	v_lshl_add_u64 v[140:141], v[140:141], 1, v[130:131]
	v_lshl_add_u64 v[142:143], v[128:129], 1, v[130:131]
	global_load_dwordx4 v[164:167], v[138:139], off offset:256
	global_load_dwordx4 v[168:171], v[138:139], off
	global_load_dwordx4 v[172:175], v[136:137], off offset:256
	global_load_dwordx4 v[176:179], v[136:137], off
	global_load_dwordx4 v[180:183], v[134:135], off offset:256
	global_load_dwordx4 v[184:187], v[134:135], off
	global_load_dwordx4 v[188:191], v[132:133], off offset:256
	global_load_dwordx4 v[192:195], v[132:133], off
	global_load_dwordx4 v[128:131], v[142:143], off offset:256
	s_nop 0
	global_load_dwordx4 v[132:135], v[142:143], off
	global_load_dwordx4 v[136:139], v[140:141], off offset:256
	s_nop 0
	global_load_dwordx4 v[140:143], v[140:141], off
	s_nop 0
	global_load_dwordx4 v[148:151], v[152:153], off offset:256
	s_nop 0
	global_load_dwordx4 v[152:155], v[152:153], off
	s_nop 0
	global_load_dwordx4 v[156:159], v[160:161], off offset:256
	s_nop 0
	global_load_dwordx4 v[160:163], v[160:161], off
	v_mov_b32_e32 v199, v82
	v_pk_mov_b32 v[82:83], v[82:83], v[108:109] op_sel:[1,0]
	v_lshl_add_u32 v108, s48, 8, v202
	v_mov_b32_e32 v200, v109
	v_ashrrev_i32_e32 v109, 31, v108
	v_mov_b32_e32 v198, v81
	v_mov_b32_e32 v201, v110
	v_lshlrev_b64 v[202:203], 12, v[108:109]
	s_lshl_b32 s10, s46, 8
	s_or_b32 s10, s10, s38
	v_add_u32_e32 v196, s10, v196
	v_readlane_b32 s10, v254, 26
	v_readlane_b32 s11, v254, 27
	v_ashrrev_i32_e32 v197, 31, v196
	s_mov_b32 s46, s18
	s_mov_b32 s48, s36
	s_mov_b64 s[50:51], s[44:45]
	s_mov_b64 s[34:35], s[42:43]
	s_waitcnt vmcnt(0)
	s_nop 0
	v_cvt_f32_f16_e32 v81, v192
	v_cvt_f32_f16_e32 v108, v194
	v_cvt_f32_f16_sdwa v110, v192 dst_sel:DWORD dst_unused:UNUSED_PAD src0_sel:WORD_1
	v_cvt_f32_f16_e32 v220, v193
	v_cvt_f32_f16_sdwa v224, v193 dst_sel:DWORD dst_unused:UNUSED_PAD src0_sel:WORD_1
	v_cvt_f32_f16_sdwa v194, v194 dst_sel:DWORD dst_unused:UNUSED_PAD src0_sel:WORD_1
	v_cvt_f32_f16_e32 v221, v195
	v_rcp_f32_e32 v81, v81
	v_rcp_f32_e32 v109, v108
	v_rcp_f32_e32 v192, v110
	v_rcp_f32_e32 v193, v220
	v_rcp_f32_e32 v108, v224
	v_cvt_f32_f16_sdwa v225, v195 dst_sel:DWORD dst_unused:UNUSED_PAD src0_sel:WORD_1
	v_rcp_f32_e32 v194, v194
	v_rcp_f32_e32 v195, v221
	v_fma_mixlo_f16 v220, v80, v81, 0
	v_pk_mul_f32 v[80:81], v[198:199], v[192:193]
	v_pk_mul_f32 v[82:83], v[82:83], v[108:109]
	v_cvt_pk_f16_f32 v80, v80, v81
	v_cvt_pk_f16_f32 v82, v82, v83
	v_pack_b32_f16 v83, v220, v80
	v_alignbit_b32 v80, v82, v80, 16
	v_pk_mul_f32 v[192:193], v[200:201], v[194:195]
	v_lshrrev_b32_e32 v109, 4, v80
	v_cvt_pk_f16_f32 v81, v192, v193
	v_and_b32_e32 v109, 0x10001, v109
	v_alignbit_b32 v82, v81, v82, 16
	v_add3_u32 v80, v80, v109, s21
	v_rcp_f32_e32 v110, v225
	v_and_b32_e32 v109, 0xfff0fff0, v80
	v_lshrrev_b32_e32 v80, 4, v82
	v_and_b32_e32 v80, 0x10001, v80
	v_add3_u32 v80, v82, v80, s21
	v_cvt_f32_f16_e32 v82, v188
	v_lshrrev_b32_e32 v81, 16, v81
	v_fma_mixhi_f16 v81, v111, v110, 0
	v_and_b32_e32 v110, 0xfff0fff0, v80
	v_lshrrev_b32_e32 v80, 4, v81
	v_lshrrev_b32_e32 v108, 4, v83
	v_and_b32_e32 v80, 0x10001, v80
	v_rcp_f32_e32 v82, v82
	v_and_b32_e32 v108, 0x10001, v108
	v_add3_u32 v80, v81, v80, s21
	v_add3_u32 v83, v83, v108, s21
	v_and_b32_e32 v111, 0xfff0fff0, v80
	v_lshl_add_u64 v[80:81], s[10:11], 0, v[202:203]
	v_and_b32_e32 v108, 0xfff0fff0, v83
	v_lshl_add_u64 v[80:81], v[196:197], 1, v[80:81]
	global_store_dwordx4 v[80:81], v[108:111], off
	v_fma_mixlo_f16 v82, v72, v82, 0
	v_cvt_f32_f16_e32 v72, v190
	v_cvt_f32_f16_sdwa v108, v188 dst_sel:DWORD dst_unused:UNUSED_PAD src0_sel:WORD_1
	v_cvt_f32_f16_sdwa v109, v190 dst_sel:DWORD dst_unused:UNUSED_PAD src0_sel:WORD_1
	v_cvt_f32_f16_e32 v110, v189
	v_rcp_f32_e32 v83, v72
	v_rcp_f32_e32 v108, v108
	v_rcp_f32_e32 v72, v109
	v_rcp_f32_e32 v109, v110
	v_mov_b32_e32 v110, v73
	v_mov_b32_e32 v111, v74
	v_cvt_f32_f16_e32 v73, v191
	v_pk_mul_f32 v[108:109], v[110:111], v[108:109]
	s_mov_b64 s[10:11], 0x10000
	v_cvt_pk_f16_f32 v74, v108, v109
	v_pack_b32_f16 v110, v82, v74
	v_cvt_f32_f16_sdwa v82, v189 dst_sel:DWORD dst_unused:UNUSED_PAD src0_sel:WORD_1
	v_rcp_f32_e32 v73, v73
	v_mov_b32_e32 v108, v89
	v_mov_b32_e32 v109, v90
	v_rcp_f32_e32 v82, v82
	v_pk_mul_f32 v[72:73], v[108:109], v[72:73]
	v_cvt_f32_f16_sdwa v90, v191 dst_sel:DWORD dst_unused:UNUSED_PAD src0_sel:WORD_1
	v_cvt_pk_f16_f32 v89, v72, v73
	v_pk_mov_b32 v[72:73], v[74:75], v[88:89] op_sel:[1,0]
	s_nop 0
	v_pk_mul_f32 v[72:73], v[72:73], v[82:83]
	v_lshrrev_b32_e32 v82, 16, v89
	v_cvt_pk_f16_f32 v72, v72, v73
	v_rcp_f32_e32 v73, v90
	v_alignbit_b32 v74, v72, v74, 16
	v_alignbit_b32 v75, v89, v72, 16
	v_lshrrev_b32_e32 v72, 4, v110
	v_fma_mixhi_f16 v82, v91, v73, 0
	v_lshrrev_b32_e32 v73, 4, v74
	v_and_b32_e32 v73, 0x10001, v73
	v_add3_u32 v73, v74, v73, s21
	v_lshrrev_b32_e32 v74, 4, v75
	v_and_b32_e32 v74, 0x10001, v74
	v_add3_u32 v74, v75, v74, s21
	v_cvt_f32_f16_e32 v75, v184
	v_lshrrev_b32_e32 v83, 4, v82
	v_and_b32_e32 v72, 0x10001, v72
	v_and_b32_e32 v83, 0x10001, v83
	v_rcp_f32_e32 v88, v75
	v_add3_u32 v72, v110, v72, s21
	v_add3_u32 v75, v82, v83, s21
	v_and_b32_e32 v72, 0xfff0fff0, v72
	v_and_b32_e32 v73, 0xfff0fff0, v73
	v_and_b32_e32 v74, 0xfff0fff0, v74
	v_and_b32_e32 v75, 0xfff0fff0, v75
	global_store_dwordx4 v[80:81], v[72:75], off offset:256
	v_cvt_f32_f16_e32 v82, v185
	v_mov_b32_e32 v83, v58
	v_fma_mixlo_f16 v72, v56, v88, 0
	v_cvt_f32_f16_e32 v56, v186
	v_cvt_f32_f16_sdwa v74, v184 dst_sel:DWORD dst_unused:UNUSED_PAD src0_sel:WORD_1
	v_cvt_f32_f16_sdwa v75, v186 dst_sel:DWORD dst_unused:UNUSED_PAD src0_sel:WORD_1
	v_rcp_f32_e32 v73, v56
	v_rcp_f32_e32 v74, v74
	v_rcp_f32_e32 v56, v75
	v_rcp_f32_e32 v75, v82
	v_mov_b32_e32 v82, v57
	v_cvt_f32_f16_e32 v57, v187
	v_pk_mul_f32 v[74:75], v[82:83], v[74:75]
	s_nop 0
	v_cvt_pk_f16_f32 v58, v74, v75
	v_pack_b32_f16 v82, v72, v58
	v_cvt_f32_f16_sdwa v72, v185 dst_sel:DWORD dst_unused:UNUSED_PAD src0_sel:WORD_1
	v_rcp_f32_e32 v57, v57
	v_mov_b32_e32 v74, v69
	v_mov_b32_e32 v75, v70
	v_rcp_f32_e32 v72, v72
	v_pk_mul_f32 v[56:57], v[74:75], v[56:57]
	v_cvt_f32_f16_sdwa v70, v187 dst_sel:DWORD dst_unused:UNUSED_PAD src0_sel:WORD_1
	v_cvt_pk_f16_f32 v69, v56, v57
	v_pk_mov_b32 v[56:57], v[58:59], v[68:69] op_sel:[1,0]
	v_lshrrev_b32_e32 v68, 16, v69
	v_pk_mul_f32 v[56:57], v[56:57], v[72:73]
	s_nop 0
	v_cvt_pk_f16_f32 v56, v56, v57
	v_rcp_f32_e32 v57, v70
	v_alignbit_b32 v58, v56, v58, 16
	v_alignbit_b32 v59, v69, v56, 16
	v_cvt_f32_f16_e32 v70, v180
	v_fma_mixhi_f16 v68, v71, v57, 0
	v_lshrrev_b32_e32 v57, 4, v58
	v_and_b32_e32 v57, 0x10001, v57
	v_add3_u32 v57, v58, v57, s21
	v_lshrrev_b32_e32 v58, 4, v59
	v_and_b32_e32 v58, 0x10001, v58
	v_add3_u32 v58, v59, v58, s21
	v_lshrrev_b32_e32 v59, 4, v68
	v_lshrrev_b32_e32 v56, 4, v82
	v_and_b32_e32 v59, 0x10001, v59
	v_rcp_f32_e32 v72, v70
	v_and_b32_e32 v56, 0x10001, v56
	v_add3_u32 v59, v68, v59, s21
	v_lshl_add_u64 v[68:69], v[80:81], 0, s[10:11]
	s_mov_b32 s10, 0x10000
	v_add3_u32 v56, v82, v56, s21
	v_add_co_u32_e32 v70, vcc, s10, v80
	v_and_b32_e32 v56, 0xfff0fff0, v56
	v_and_b32_e32 v57, 0xfff0fff0, v57
	v_and_b32_e32 v58, 0xfff0fff0, v58
	v_and_b32_e32 v59, 0xfff0fff0, v59
	v_addc_co_u32_e32 v71, vcc, 0, v81, vcc
	global_store_dwordx4 v[70:71], v[56:59], off
	v_cvt_f32_f16_e32 v70, v181
	v_mov_b32_e32 v71, v42
	v_fma_mixlo_f16 v56, v40, v72, 0
	v_cvt_f32_f16_e32 v40, v182
	v_cvt_f32_f16_sdwa v58, v180 dst_sel:DWORD dst_unused:UNUSED_PAD src0_sel:WORD_1
	v_cvt_f32_f16_sdwa v59, v182 dst_sel:DWORD dst_unused:UNUSED_PAD src0_sel:WORD_1
	s_mov_b64 s[10:11], 0x20000
	v_rcp_f32_e32 v57, v40
	v_rcp_f32_e32 v58, v58
	v_rcp_f32_e32 v40, v59
	v_rcp_f32_e32 v59, v70
	v_mov_b32_e32 v70, v41
	v_cvt_f32_f16_e32 v41, v183
	v_pk_mul_f32 v[58:59], v[70:71], v[58:59]
	s_nop 0
	v_cvt_pk_f16_f32 v42, v58, v59
	v_pack_b32_f16 v70, v56, v42
	v_cvt_f32_f16_sdwa v56, v181 dst_sel:DWORD dst_unused:UNUSED_PAD src0_sel:WORD_1
	v_rcp_f32_e32 v41, v41
	v_mov_b32_e32 v58, v53
	v_mov_b32_e32 v59, v54
	v_rcp_f32_e32 v56, v56
	v_pk_mul_f32 v[40:41], v[58:59], v[40:41]
	v_cvt_f32_f16_sdwa v54, v183 dst_sel:DWORD dst_unused:UNUSED_PAD src0_sel:WORD_1
	v_cvt_pk_f16_f32 v53, v40, v41
	v_pk_mov_b32 v[40:41], v[42:43], v[52:53] op_sel:[1,0]
	v_lshrrev_b32_e32 v52, 16, v53
	v_pk_mul_f32 v[40:41], v[40:41], v[56:57]
	s_nop 0
	v_cvt_pk_f16_f32 v40, v40, v41
	v_rcp_f32_e32 v41, v54
	v_alignbit_b32 v42, v40, v42, 16
	v_alignbit_b32 v43, v53, v40, 16
	v_lshrrev_b32_e32 v40, 4, v70
	v_fma_mixhi_f16 v52, v55, v41, 0
	v_lshrrev_b32_e32 v41, 4, v42
	v_and_b32_e32 v41, 0x10001, v41
	v_add3_u32 v41, v42, v41, s21
	v_lshrrev_b32_e32 v42, 4, v43
	v_and_b32_e32 v42, 0x10001, v42
	v_add3_u32 v42, v43, v42, s21
	v_cvt_f32_f16_e32 v43, v176
	v_lshrrev_b32_e32 v53, 4, v52
	v_and_b32_e32 v40, 0x10001, v40
	v_and_b32_e32 v53, 0x10001, v53
	v_rcp_f32_e32 v54, v43
	v_add3_u32 v40, v70, v40, s21
	v_add3_u32 v43, v52, v53, s21
	v_and_b32_e32 v40, 0xfff0fff0, v40
	v_and_b32_e32 v41, 0xfff0fff0, v41
	v_and_b32_e32 v42, 0xfff0fff0, v42
	v_and_b32_e32 v43, 0xfff0fff0, v43
	global_store_dwordx4 v[68:69], v[40:43], off offset:256
	v_cvt_f32_f16_e32 v52, v177
	v_mov_b32_e32 v53, v30
	v_fma_mixlo_f16 v40, v28, v54, 0
	v_cvt_f32_f16_e32 v28, v178
	v_cvt_f32_f16_sdwa v42, v176 dst_sel:DWORD dst_unused:UNUSED_PAD src0_sel:WORD_1
	v_cvt_f32_f16_sdwa v43, v178 dst_sel:DWORD dst_unused:UNUSED_PAD src0_sel:WORD_1
	v_rcp_f32_e32 v41, v28
	v_rcp_f32_e32 v42, v42
	v_rcp_f32_e32 v28, v43
	v_rcp_f32_e32 v43, v52
	v_mov_b32_e32 v52, v29
	v_cvt_f32_f16_e32 v29, v179
	v_pk_mul_f32 v[42:43], v[52:53], v[42:43]
	s_nop 0
	v_cvt_pk_f16_f32 v30, v42, v43
	v_pack_b32_f16 v52, v40, v30
	v_cvt_f32_f16_sdwa v40, v177 dst_sel:DWORD dst_unused:UNUSED_PAD src0_sel:WORD_1
	v_rcp_f32_e32 v29, v29
	v_mov_b32_e32 v42, v37
	v_mov_b32_e32 v43, v38
	v_rcp_f32_e32 v40, v40
	v_pk_mul_f32 v[28:29], v[42:43], v[28:29]
	v_cvt_f32_f16_sdwa v38, v179 dst_sel:DWORD dst_unused:UNUSED_PAD src0_sel:WORD_1
	v_cvt_pk_f16_f32 v37, v28, v29
	v_pk_mov_b32 v[28:29], v[30:31], v[36:37] op_sel:[1,0]
	v_lshrrev_b32_e32 v36, 16, v37
	v_pk_mul_f32 v[28:29], v[28:29], v[40:41]
	s_nop 0
	v_cvt_pk_f16_f32 v28, v28, v29
	v_rcp_f32_e32 v29, v38
	v_alignbit_b32 v30, v28, v30, 16
	v_alignbit_b32 v31, v37, v28, 16
	v_cvt_f32_f16_e32 v38, v172
	v_fma_mixhi_f16 v36, v39, v29, 0
	v_lshrrev_b32_e32 v29, 4, v30
	v_and_b32_e32 v29, 0x10001, v29
	v_add3_u32 v29, v30, v29, s21
	v_lshrrev_b32_e32 v30, 4, v31
	v_and_b32_e32 v30, 0x10001, v30
	v_add3_u32 v30, v31, v30, s21
	v_lshrrev_b32_e32 v31, 4, v36
	v_lshrrev_b32_e32 v28, 4, v52
	v_and_b32_e32 v31, 0x10001, v31
	v_rcp_f32_e32 v40, v38
	v_and_b32_e32 v28, 0x10001, v28
	v_add3_u32 v31, v36, v31, s21
	v_lshl_add_u64 v[36:37], v[80:81], 0, s[10:11]
	s_mov_b32 s10, 0x20000
	v_add3_u32 v28, v52, v28, s21
	v_add_co_u32_e32 v38, vcc, s10, v80
	v_and_b32_e32 v28, 0xfff0fff0, v28
	v_and_b32_e32 v29, 0xfff0fff0, v29
	v_and_b32_e32 v30, 0xfff0fff0, v30
	v_and_b32_e32 v31, 0xfff0fff0, v31
	v_addc_co_u32_e32 v39, vcc, 0, v81, vcc
	global_store_dwordx4 v[38:39], v[28:31], off
	v_cvt_f32_f16_e32 v38, v173
	v_mov_b32_e32 v39, v22
	v_fma_mixlo_f16 v28, v20, v40, 0
	v_cvt_f32_f16_e32 v20, v174
	v_cvt_f32_f16_sdwa v30, v172 dst_sel:DWORD dst_unused:UNUSED_PAD src0_sel:WORD_1
	v_cvt_f32_f16_sdwa v31, v174 dst_sel:DWORD dst_unused:UNUSED_PAD src0_sel:WORD_1
	s_mov_b64 s[10:11], 0x30000
	v_rcp_f32_e32 v29, v20
	v_rcp_f32_e32 v30, v30
	v_rcp_f32_e32 v20, v31
	v_rcp_f32_e32 v31, v38
	v_mov_b32_e32 v38, v21
	v_cvt_f32_f16_e32 v21, v175
	v_pk_mul_f32 v[30:31], v[38:39], v[30:31]
	s_nop 0
	v_cvt_pk_f16_f32 v22, v30, v31
	v_pack_b32_f16 v38, v28, v22
	v_cvt_f32_f16_sdwa v28, v173 dst_sel:DWORD dst_unused:UNUSED_PAD src0_sel:WORD_1
	v_rcp_f32_e32 v21, v21
	v_mov_b32_e32 v30, v25
	v_mov_b32_e32 v31, v26
	v_rcp_f32_e32 v28, v28
	v_pk_mul_f32 v[20:21], v[30:31], v[20:21]
	v_cvt_f32_f16_sdwa v26, v175 dst_sel:DWORD dst_unused:UNUSED_PAD src0_sel:WORD_1
	v_cvt_pk_f16_f32 v25, v20, v21
	v_pk_mov_b32 v[20:21], v[22:23], v[24:25] op_sel:[1,0]
	v_lshrrev_b32_e32 v24, 16, v25
	v_pk_mul_f32 v[20:21], v[20:21], v[28:29]
	s_nop 0
	v_cvt_pk_f16_f32 v20, v20, v21
	v_rcp_f32_e32 v21, v26
	v_alignbit_b32 v22, v20, v22, 16
	v_alignbit_b32 v23, v25, v20, 16
	v_lshrrev_b32_e32 v20, 4, v38
	v_fma_mixhi_f16 v24, v27, v21, 0
	v_lshrrev_b32_e32 v21, 4, v22
	v_and_b32_e32 v21, 0x10001, v21
	v_add3_u32 v21, v22, v21, s21
	v_lshrrev_b32_e32 v22, 4, v23
	v_and_b32_e32 v22, 0x10001, v22
	v_add3_u32 v22, v23, v22, s21
	v_cvt_f32_f16_e32 v23, v168
	v_lshrrev_b32_e32 v25, 4, v24
	v_and_b32_e32 v20, 0x10001, v20
	v_and_b32_e32 v25, 0x10001, v25
	v_rcp_f32_e32 v26, v23
	v_add3_u32 v20, v38, v20, s21
	v_add3_u32 v23, v24, v25, s21
	v_and_b32_e32 v20, 0xfff0fff0, v20
	v_and_b32_e32 v21, 0xfff0fff0, v21
	v_and_b32_e32 v22, 0xfff0fff0, v22
	v_and_b32_e32 v23, 0xfff0fff0, v23
	global_store_dwordx4 v[36:37], v[20:23], off offset:256
	v_cvt_f32_f16_e32 v24, v169
	v_mov_b32_e32 v25, v18
	v_fma_mixlo_f16 v20, v16, v26, 0
	v_cvt_f32_f16_e32 v16, v170
	v_cvt_f32_f16_sdwa v22, v168 dst_sel:DWORD dst_unused:UNUSED_PAD src0_sel:WORD_1
	v_cvt_f32_f16_sdwa v23, v170 dst_sel:DWORD dst_unused:UNUSED_PAD src0_sel:WORD_1
	v_rcp_f32_e32 v21, v16
	v_rcp_f32_e32 v22, v22
	v_rcp_f32_e32 v16, v23
	v_rcp_f32_e32 v23, v24
	v_mov_b32_e32 v24, v17
	v_cvt_f32_f16_e32 v17, v171
	v_pk_mul_f32 v[22:23], v[24:25], v[22:23]
	s_nop 0
	v_cvt_pk_f16_f32 v18, v22, v23
	v_pack_b32_f16 v24, v20, v18
	v_rcp_f32_e32 v17, v17
	v_cvt_f32_f16_sdwa v20, v169 dst_sel:DWORD dst_unused:UNUSED_PAD src0_sel:WORD_1
	v_mov_b32_e32 v22, v13
	v_mov_b32_e32 v23, v14
	v_pk_mul_f32 v[16:17], v[22:23], v[16:17]
	v_rcp_f32_e32 v20, v20
	v_cvt_pk_f16_f32 v14, v16, v17
	v_cvt_f32_f16_sdwa v16, v171 dst_sel:DWORD dst_unused:UNUSED_PAD src0_sel:WORD_1
	v_pk_mov_b32 v[12:13], v[18:19], v[12:13] op_sel:[1,0]
	s_nop 0
	v_pk_mul_f32 v[12:13], v[12:13], v[20:21]
	s_nop 0
	v_cvt_pk_f16_f32 v12, v12, v13
	v_rcp_f32_e32 v13, v16
	v_alignbit_b32 v16, v12, v18, 16
	v_lshrrev_b32_e32 v18, 16, v14
	v_alignbit_b32 v17, v14, v12, 16
	v_fma_mixhi_f16 v18, v15, v13, 0
	v_lshrrev_b32_e32 v15, 4, v18
	v_and_b32_e32 v15, 0x10001, v15
	v_add3_u32 v15, v18, v15, s21
	v_cvt_f32_f16_e32 v18, v164
	v_lshrrev_b32_e32 v13, 4, v16
	v_lshrrev_b32_e32 v14, 4, v17
	v_lshrrev_b32_e32 v12, 4, v24
	v_and_b32_e32 v13, 0x10001, v13
	v_and_b32_e32 v14, 0x10001, v14
	v_rcp_f32_e32 v20, v18
	v_and_b32_e32 v12, 0x10001, v12
	v_add3_u32 v13, v16, v13, s21
	v_add3_u32 v14, v17, v14, s21
	v_lshl_add_u64 v[16:17], v[80:81], 0, s[10:11]
	s_mov_b32 s10, 0x30000
	v_add3_u32 v12, v24, v12, s21
	v_add_co_u32_e32 v18, vcc, s10, v80
	v_and_b32_e32 v12, 0xfff0fff0, v12
	v_and_b32_e32 v13, 0xfff0fff0, v13
	v_and_b32_e32 v14, 0xfff0fff0, v14
	v_and_b32_e32 v15, 0xfff0fff0, v15
	v_addc_co_u32_e32 v19, vcc, 0, v81, vcc
	global_store_dwordx4 v[18:19], v[12:15], off
	v_cvt_f32_f16_e32 v18, v165
	v_mov_b32_e32 v19, v10
	v_fma_mixlo_f16 v12, v8, v20, 0
	v_cvt_f32_f16_e32 v8, v166
	v_cvt_f32_f16_sdwa v14, v164 dst_sel:DWORD dst_unused:UNUSED_PAD src0_sel:WORD_1
	v_cvt_f32_f16_sdwa v15, v166 dst_sel:DWORD dst_unused:UNUSED_PAD src0_sel:WORD_1
	s_mov_b64 s[10:11], 0x80000
	v_rcp_f32_e32 v13, v8
	v_rcp_f32_e32 v14, v14
	v_rcp_f32_e32 v8, v15
	v_rcp_f32_e32 v15, v18
	v_mov_b32_e32 v18, v9
	v_cvt_f32_f16_e32 v9, v167
	v_pk_mul_f32 v[14:15], v[18:19], v[14:15]
	s_nop 0
	v_cvt_pk_f16_f32 v10, v14, v15
	v_pack_b32_f16 v18, v12, v10
	v_rcp_f32_e32 v9, v9
	v_cvt_f32_f16_sdwa v12, v165 dst_sel:DWORD dst_unused:UNUSED_PAD src0_sel:WORD_1
	v_mov_b32_e32 v14, v5
	v_mov_b32_e32 v15, v6
	v_pk_mul_f32 v[8:9], v[14:15], v[8:9]
	v_rcp_f32_e32 v12, v12
	v_cvt_pk_f16_f32 v6, v8, v9
	v_cvt_f32_f16_sdwa v8, v167 dst_sel:DWORD dst_unused:UNUSED_PAD src0_sel:WORD_1
	v_pk_mov_b32 v[4:5], v[10:11], v[4:5] op_sel:[1,0]
	v_mov_b32_e32 v11, v126
	v_pk_mul_f32 v[4:5], v[4:5], v[12:13]
	v_mov_b32_e32 v13, v118
	v_cvt_pk_f16_f32 v4, v4, v5
	v_rcp_f32_e32 v5, v8
	v_alignbit_b32 v8, v4, v10, 16
	v_lshrrev_b32_e32 v10, 16, v6
	v_alignbit_b32 v9, v6, v4, 16
	v_fma_mixhi_f16 v10, v7, v5, 0
	v_cvt_f32_f16_e32 v7, v160
	v_lshrrev_b32_e32 v5, 4, v8
	v_lshrrev_b32_e32 v6, 4, v9
	v_and_b32_e32 v5, 0x10001, v5
	v_and_b32_e32 v6, 0x10001, v6
	v_lshrrev_b32_e32 v4, 4, v18
	v_add3_u32 v5, v8, v5, s21
	v_add3_u32 v6, v9, v6, s21
	v_lshrrev_b32_e32 v8, 4, v10
	v_rcp_f32_e32 v9, v7
	v_and_b32_e32 v4, 0x10001, v4
	v_and_b32_e32 v8, 0x10001, v8
	v_add3_u32 v4, v18, v4, s21
	v_add3_u32 v8, v10, v8, s21
	v_and_b32_e32 v4, 0xfff0fff0, v4
	v_and_b32_e32 v5, 0xfff0fff0, v5
	v_and_b32_e32 v6, 0xfff0fff0, v6
	v_and_b32_e32 v7, 0xfff0fff0, v8
	global_store_dwordx4 v[16:17], v[4:7], off offset:256
	v_mov_b32_e32 v10, v125
	s_nop 0
	v_fma_mixlo_f16 v4, v124, v9, 0
	v_cvt_f32_f16_sdwa v6, v160 dst_sel:DWORD dst_unused:UNUSED_PAD src0_sel:WORD_1
	v_cvt_f32_f16_sdwa v7, v162 dst_sel:DWORD dst_unused:UNUSED_PAD src0_sel:WORD_1
	v_cvt_f32_f16_e32 v9, v161
	v_cvt_f32_f16_e32 v5, v162
	v_rcp_f32_e32 v6, v6
	v_rcp_f32_e32 v8, v7
	v_rcp_f32_e32 v7, v9
	v_cvt_f32_f16_e32 v9, v163
	v_rcp_f32_e32 v5, v5
	v_pk_mul_f32 v[6:7], v[10:11], v[6:7]
	s_nop 0
	v_cvt_pk_f16_f32 v10, v6, v7
	v_pack_b32_f16 v11, v4, v10
	v_cvt_f32_f16_sdwa v4, v161 dst_sel:DWORD dst_unused:UNUSED_PAD src0_sel:WORD_1
	v_rcp_f32_e32 v9, v9
	v_mov_b32_e32 v6, v145
	v_mov_b32_e32 v7, v146
	v_rcp_f32_e32 v4, v4
	v_pk_mul_f32 v[6:7], v[6:7], v[8:9]
	v_cvt_f32_f16_sdwa v9, v163 dst_sel:DWORD dst_unused:UNUSED_PAD src0_sel:WORD_1
	v_cvt_pk_f16_f32 v8, v6, v7
	v_pk_mov_b32 v[6:7], v[126:127], v[144:145] op_sel:[1,0]
	s_nop 0
	v_pk_mul_f32 v[4:5], v[6:7], v[4:5]
	s_nop 0
	v_cvt_pk_f16_f32 v4, v4, v5
	v_rcp_f32_e32 v5, v9
	v_alignbit_b32 v6, v4, v10, 16
	v_alignbit_b32 v7, v8, v4, 16
	v_lshrrev_b32_e32 v8, 16, v8
	v_fma_mixhi_f16 v8, v147, v5, 0
	v_lshrrev_b32_e32 v5, 4, v6
	v_and_b32_e32 v5, 0x10001, v5
	v_add3_u32 v5, v6, v5, s21
	v_lshrrev_b32_e32 v6, 4, v7
	v_and_b32_e32 v6, 0x10001, v6
	v_cvt_f32_f16_e32 v10, v156
	v_add3_u32 v6, v7, v6, s21
	v_lshrrev_b32_e32 v7, 4, v8
	v_lshrrev_b32_e32 v4, 4, v11
	v_and_b32_e32 v7, 0x10001, v7
	v_and_b32_e32 v4, 0x10001, v4
	v_add3_u32 v7, v8, v7, s21
	v_lshl_add_u64 v[8:9], v[80:81], 0, s[10:11]
	s_mov_b32 s10, 0x80000
	v_add3_u32 v4, v11, v4, s21
	v_rcp_f32_e32 v12, v10
	v_add_co_u32_e32 v10, vcc, s10, v80
	v_and_b32_e32 v4, 0xfff0fff0, v4
	v_and_b32_e32 v5, 0xfff0fff0, v5
	v_and_b32_e32 v6, 0xfff0fff0, v6
	v_and_b32_e32 v7, 0xfff0fff0, v7
	v_addc_co_u32_e32 v11, vcc, 0, v81, vcc
	global_store_dwordx4 v[10:11], v[4:7], off
	v_cvt_f32_f16_e32 v11, v157
	s_mov_b64 s[10:11], 0x90000
	v_cvt_f32_f16_sdwa v6, v156 dst_sel:DWORD dst_unused:UNUSED_PAD src0_sel:WORD_1
	v_cvt_f32_f16_sdwa v7, v158 dst_sel:DWORD dst_unused:UNUSED_PAD src0_sel:WORD_1
	v_fma_mixlo_f16 v4, v116, v12, 0
	v_mov_b32_e32 v12, v117
	v_rcp_f32_e32 v6, v6
	v_rcp_f32_e32 v10, v7
	v_rcp_f32_e32 v7, v11
	v_cvt_f32_f16_e32 v11, v159
	v_cvt_f32_f16_e32 v5, v158
	v_pk_mul_f32 v[6:7], v[12:13], v[6:7]
	s_nop 0
	v_cvt_pk_f16_f32 v12, v6, v7
	v_pack_b32_f16 v13, v4, v12
	v_cvt_f32_f16_sdwa v4, v157 dst_sel:DWORD dst_unused:UNUSED_PAD src0_sel:WORD_1
	v_rcp_f32_e32 v11, v11
	v_rcp_f32_e32 v5, v5
	v_mov_b32_e32 v6, v121
	v_mov_b32_e32 v7, v122
	v_rcp_f32_e32 v4, v4
	v_pk_mul_f32 v[6:7], v[6:7], v[10:11]
	v_cvt_f32_f16_sdwa v11, v159 dst_sel:DWORD dst_unused:UNUSED_PAD src0_sel:WORD_1
	v_cvt_pk_f16_f32 v10, v6, v7
	v_pk_mov_b32 v[6:7], v[118:119], v[120:121] op_sel:[1,0]
	s_nop 0
	v_pk_mul_f32 v[4:5], v[6:7], v[4:5]
	s_nop 0
	v_cvt_pk_f16_f32 v4, v4, v5
	v_rcp_f32_e32 v5, v11
	v_alignbit_b32 v6, v4, v12, 16
	v_alignbit_b32 v7, v10, v4, 16
	v_lshrrev_b32_e32 v10, 16, v10
	v_fma_mixhi_f16 v10, v123, v5, 0
	v_lshrrev_b32_e32 v5, 4, v6
	v_and_b32_e32 v5, 0x10001, v5
	v_add3_u32 v5, v6, v5, s21
	v_lshrrev_b32_e32 v6, 4, v7
	v_and_b32_e32 v6, 0x10001, v6
	v_add3_u32 v6, v7, v6, s21
	v_cvt_f32_f16_e32 v7, v152
	v_lshrrev_b32_e32 v4, 4, v13
	v_lshrrev_b32_e32 v11, 4, v10
	v_and_b32_e32 v4, 0x10001, v4
	v_and_b32_e32 v11, 0x10001, v11
	v_add3_u32 v4, v13, v4, s21
	v_rcp_f32_e32 v12, v7
	v_add3_u32 v7, v10, v11, s21
	v_and_b32_e32 v4, 0xfff0fff0, v4
	v_and_b32_e32 v5, 0xfff0fff0, v5
	v_and_b32_e32 v6, 0xfff0fff0, v6
	v_and_b32_e32 v7, 0xfff0fff0, v7
	global_store_dwordx4 v[8:9], v[4:7], off offset:256
	v_cvt_f32_f16_e32 v9, v153
	v_mov_b32_e32 v10, v105
	v_cvt_f32_f16_sdwa v6, v152 dst_sel:DWORD dst_unused:UNUSED_PAD src0_sel:WORD_1
	v_cvt_f32_f16_sdwa v7, v154 dst_sel:DWORD dst_unused:UNUSED_PAD src0_sel:WORD_1
	v_mov_b32_e32 v11, v106
	v_fma_mixlo_f16 v4, v104, v12, 0
	v_rcp_f32_e32 v6, v6
	v_rcp_f32_e32 v8, v7
	v_rcp_f32_e32 v7, v9
	v_cvt_f32_f16_e32 v9, v155
	v_cvt_f32_f16_e32 v5, v154
	v_mov_b32_e32 v13, v98
	v_pk_mul_f32 v[6:7], v[10:11], v[6:7]
	v_rcp_f32_e32 v9, v9
	v_cvt_pk_f16_f32 v10, v6, v7
	v_pack_b32_f16 v11, v4, v10
	v_cvt_f32_f16_sdwa v4, v153 dst_sel:DWORD dst_unused:UNUSED_PAD src0_sel:WORD_1
	v_rcp_f32_e32 v5, v5
	v_mov_b32_e32 v6, v113
	v_mov_b32_e32 v7, v114
	v_rcp_f32_e32 v4, v4
	v_pk_mul_f32 v[6:7], v[6:7], v[8:9]
	v_cvt_f32_f16_sdwa v9, v155 dst_sel:DWORD dst_unused:UNUSED_PAD src0_sel:WORD_1
	v_cvt_pk_f16_f32 v8, v6, v7
	v_pk_mov_b32 v[6:7], v[106:107], v[112:113] op_sel:[1,0]
	s_nop 0
	v_pk_mul_f32 v[4:5], v[6:7], v[4:5]
	s_nop 0
	v_cvt_pk_f16_f32 v4, v4, v5
	v_rcp_f32_e32 v5, v9
	v_alignbit_b32 v6, v4, v10, 16
	v_alignbit_b32 v7, v8, v4, 16
	v_lshrrev_b32_e32 v8, 16, v8
	v_fma_mixhi_f16 v8, v115, v5, 0
	v_lshrrev_b32_e32 v5, 4, v6
	v_and_b32_e32 v5, 0x10001, v5
	v_add3_u32 v5, v6, v5, s21
	v_lshrrev_b32_e32 v6, 4, v7
	v_and_b32_e32 v6, 0x10001, v6
	v_cvt_f32_f16_e32 v10, v148
	v_add3_u32 v6, v7, v6, s21
	v_lshrrev_b32_e32 v7, 4, v8
	v_lshrrev_b32_e32 v4, 4, v11
	v_and_b32_e32 v7, 0x10001, v7
	v_and_b32_e32 v4, 0x10001, v4
	v_add3_u32 v7, v8, v7, s21
	v_lshl_add_u64 v[8:9], v[80:81], 0, s[10:11]
	s_mov_b32 s10, 0x90000
	v_add3_u32 v4, v11, v4, s21
	v_rcp_f32_e32 v12, v10
	v_add_co_u32_e32 v10, vcc, s10, v80
	v_and_b32_e32 v4, 0xfff0fff0, v4
	v_and_b32_e32 v5, 0xfff0fff0, v5
	v_and_b32_e32 v6, 0xfff0fff0, v6
	v_and_b32_e32 v7, 0xfff0fff0, v7
	v_addc_co_u32_e32 v11, vcc, 0, v81, vcc
	global_store_dwordx4 v[10:11], v[4:7], off
	v_cvt_f32_f16_e32 v11, v149
	s_mov_b64 s[10:11], 0xa0000
	v_cvt_f32_f16_sdwa v6, v148 dst_sel:DWORD dst_unused:UNUSED_PAD src0_sel:WORD_1
	v_cvt_f32_f16_sdwa v7, v150 dst_sel:DWORD dst_unused:UNUSED_PAD src0_sel:WORD_1
	v_fma_mixlo_f16 v4, v96, v12, 0
	v_mov_b32_e32 v12, v97
	v_rcp_f32_e32 v6, v6
	v_rcp_f32_e32 v10, v7
	v_rcp_f32_e32 v7, v11
	v_cvt_f32_f16_e32 v11, v151
	v_cvt_f32_f16_e32 v5, v150
	v_pk_mul_f32 v[6:7], v[12:13], v[6:7]
	s_nop 0
	v_cvt_pk_f16_f32 v12, v6, v7
	v_pack_b32_f16 v13, v4, v12
	v_cvt_f32_f16_sdwa v4, v149 dst_sel:DWORD dst_unused:UNUSED_PAD src0_sel:WORD_1
	v_rcp_f32_e32 v11, v11
	v_rcp_f32_e32 v5, v5
	v_mov_b32_e32 v6, v101
	v_mov_b32_e32 v7, v102
	v_rcp_f32_e32 v4, v4
	v_pk_mul_f32 v[6:7], v[6:7], v[10:11]
	v_cvt_f32_f16_sdwa v11, v151 dst_sel:DWORD dst_unused:UNUSED_PAD src0_sel:WORD_1
	v_cvt_pk_f16_f32 v10, v6, v7
	v_pk_mov_b32 v[6:7], v[98:99], v[100:101] op_sel:[1,0]
	s_nop 0
	v_pk_mul_f32 v[4:5], v[6:7], v[4:5]
	s_nop 0
	v_cvt_pk_f16_f32 v4, v4, v5
	v_rcp_f32_e32 v5, v11
	v_alignbit_b32 v6, v4, v12, 16
	v_alignbit_b32 v7, v10, v4, 16
	v_lshrrev_b32_e32 v10, 16, v10
	v_fma_mixhi_f16 v10, v103, v5, 0
	v_lshrrev_b32_e32 v5, 4, v6
	v_and_b32_e32 v5, 0x10001, v5
	v_add3_u32 v5, v6, v5, s21
	v_lshrrev_b32_e32 v6, 4, v7
	v_and_b32_e32 v6, 0x10001, v6
	v_add3_u32 v6, v7, v6, s21
	v_cvt_f32_f16_e32 v7, v140
	v_lshrrev_b32_e32 v4, 4, v13
	v_lshrrev_b32_e32 v11, 4, v10
	v_and_b32_e32 v4, 0x10001, v4
	v_and_b32_e32 v11, 0x10001, v11
	v_add3_u32 v4, v13, v4, s21
	v_rcp_f32_e32 v12, v7
	v_add3_u32 v7, v10, v11, s21
	v_and_b32_e32 v4, 0xfff0fff0, v4
	v_and_b32_e32 v5, 0xfff0fff0, v5
	v_and_b32_e32 v6, 0xfff0fff0, v6
	v_and_b32_e32 v7, 0xfff0fff0, v7
	global_store_dwordx4 v[8:9], v[4:7], off offset:256
	v_cvt_f32_f16_e32 v9, v141
	v_mov_b32_e32 v10, v85
	v_cvt_f32_f16_sdwa v6, v140 dst_sel:DWORD dst_unused:UNUSED_PAD src0_sel:WORD_1
	v_cvt_f32_f16_sdwa v7, v142 dst_sel:DWORD dst_unused:UNUSED_PAD src0_sel:WORD_1
	v_mov_b32_e32 v11, v86
	v_fma_mixlo_f16 v4, v84, v12, 0
	v_rcp_f32_e32 v6, v6
	v_rcp_f32_e32 v8, v7
	v_rcp_f32_e32 v7, v9
	v_cvt_f32_f16_e32 v9, v143
	v_cvt_f32_f16_e32 v5, v142
	v_mov_b32_e32 v13, v66
	v_pk_mul_f32 v[6:7], v[10:11], v[6:7]
	v_rcp_f32_e32 v9, v9
	v_cvt_pk_f16_f32 v10, v6, v7
	v_pack_b32_f16 v11, v4, v10
	v_cvt_f32_f16_sdwa v4, v141 dst_sel:DWORD dst_unused:UNUSED_PAD src0_sel:WORD_1
	v_rcp_f32_e32 v5, v5
	v_mov_b32_e32 v6, v93
	v_mov_b32_e32 v7, v94
	v_rcp_f32_e32 v4, v4
	v_pk_mul_f32 v[6:7], v[6:7], v[8:9]
	v_cvt_f32_f16_sdwa v9, v143 dst_sel:DWORD dst_unused:UNUSED_PAD src0_sel:WORD_1
	v_cvt_pk_f16_f32 v8, v6, v7
	v_pk_mov_b32 v[6:7], v[86:87], v[92:93] op_sel:[1,0]
	s_nop 0
	v_pk_mul_f32 v[4:5], v[6:7], v[4:5]
	s_nop 0
	v_cvt_pk_f16_f32 v4, v4, v5
	v_rcp_f32_e32 v5, v9
	v_alignbit_b32 v6, v4, v10, 16
	v_alignbit_b32 v7, v8, v4, 16
	v_lshrrev_b32_e32 v8, 16, v8
	v_fma_mixhi_f16 v8, v95, v5, 0
	v_lshrrev_b32_e32 v5, 4, v6
	v_and_b32_e32 v5, 0x10001, v5
	v_add3_u32 v5, v6, v5, s21
	v_lshrrev_b32_e32 v6, 4, v7
	v_and_b32_e32 v6, 0x10001, v6
	v_cvt_f32_f16_e32 v10, v136
	v_add3_u32 v6, v7, v6, s21
	v_lshrrev_b32_e32 v7, 4, v8
	v_lshrrev_b32_e32 v4, 4, v11
	v_and_b32_e32 v7, 0x10001, v7
	v_and_b32_e32 v4, 0x10001, v4
	v_add3_u32 v7, v8, v7, s21
	v_lshl_add_u64 v[8:9], v[80:81], 0, s[10:11]
	s_mov_b32 s10, 0xa0000
	v_add3_u32 v4, v11, v4, s21
	v_rcp_f32_e32 v12, v10
	v_add_co_u32_e32 v10, vcc, s10, v80
	v_and_b32_e32 v4, 0xfff0fff0, v4
	v_and_b32_e32 v5, 0xfff0fff0, v5
	v_and_b32_e32 v6, 0xfff0fff0, v6
	v_and_b32_e32 v7, 0xfff0fff0, v7
	v_addc_co_u32_e32 v11, vcc, 0, v81, vcc
	global_store_dwordx4 v[10:11], v[4:7], off
	v_cvt_f32_f16_e32 v11, v137
	s_mov_b64 s[10:11], 0xb0000
	v_cvt_f32_f16_sdwa v6, v136 dst_sel:DWORD dst_unused:UNUSED_PAD src0_sel:WORD_1
	v_cvt_f32_f16_sdwa v7, v138 dst_sel:DWORD dst_unused:UNUSED_PAD src0_sel:WORD_1
	v_fma_mixlo_f16 v4, v64, v12, 0
	v_mov_b32_e32 v12, v65
	v_rcp_f32_e32 v6, v6
	v_rcp_f32_e32 v10, v7
	v_rcp_f32_e32 v7, v11
	v_cvt_f32_f16_e32 v11, v139
	v_cvt_f32_f16_e32 v5, v138
	v_pk_mul_f32 v[6:7], v[12:13], v[6:7]
	s_nop 0
	v_cvt_pk_f16_f32 v12, v6, v7
	v_pack_b32_f16 v13, v4, v12
	v_cvt_f32_f16_sdwa v4, v137 dst_sel:DWORD dst_unused:UNUSED_PAD src0_sel:WORD_1
	v_rcp_f32_e32 v11, v11
	v_rcp_f32_e32 v5, v5
	v_mov_b32_e32 v6, v77
	v_mov_b32_e32 v7, v78
	v_rcp_f32_e32 v4, v4
	v_pk_mul_f32 v[6:7], v[6:7], v[10:11]
	v_cvt_f32_f16_sdwa v11, v139 dst_sel:DWORD dst_unused:UNUSED_PAD src0_sel:WORD_1
	v_cvt_pk_f16_f32 v10, v6, v7
	v_pk_mov_b32 v[6:7], v[66:67], v[76:77] op_sel:[1,0]
	s_nop 0
	v_pk_mul_f32 v[4:5], v[6:7], v[4:5]
	s_nop 0
	v_cvt_pk_f16_f32 v4, v4, v5
	v_rcp_f32_e32 v5, v11
	v_alignbit_b32 v6, v4, v12, 16
	v_alignbit_b32 v7, v10, v4, 16
	v_lshrrev_b32_e32 v10, 16, v10
	v_fma_mixhi_f16 v10, v79, v5, 0
	v_lshrrev_b32_e32 v5, 4, v6
	v_and_b32_e32 v5, 0x10001, v5
	v_add3_u32 v5, v6, v5, s21
	v_lshrrev_b32_e32 v6, 4, v7
	v_and_b32_e32 v6, 0x10001, v6
	v_add3_u32 v6, v7, v6, s21
	v_cvt_f32_f16_e32 v7, v132
	v_lshrrev_b32_e32 v4, 4, v13
	v_lshrrev_b32_e32 v11, 4, v10
	v_and_b32_e32 v4, 0x10001, v4
	v_and_b32_e32 v11, 0x10001, v11
	v_add3_u32 v4, v13, v4, s21
	v_rcp_f32_e32 v12, v7
	v_add3_u32 v7, v10, v11, s21
	v_and_b32_e32 v4, 0xfff0fff0, v4
	v_and_b32_e32 v5, 0xfff0fff0, v5
	v_and_b32_e32 v6, 0xfff0fff0, v6
	v_and_b32_e32 v7, 0xfff0fff0, v7
	global_store_dwordx4 v[8:9], v[4:7], off offset:256
	v_cvt_f32_f16_e32 v9, v133
	v_mov_b32_e32 v10, v49
	v_cvt_f32_f16_sdwa v6, v132 dst_sel:DWORD dst_unused:UNUSED_PAD src0_sel:WORD_1
	v_cvt_f32_f16_sdwa v7, v134 dst_sel:DWORD dst_unused:UNUSED_PAD src0_sel:WORD_1
	v_mov_b32_e32 v11, v50
	v_fma_mixlo_f16 v4, v48, v12, 0
	v_rcp_f32_e32 v6, v6
	v_rcp_f32_e32 v8, v7
	v_rcp_f32_e32 v7, v9
	v_cvt_f32_f16_e32 v9, v135
	v_cvt_f32_f16_e32 v5, v134
	v_mov_b32_e32 v13, v34
	v_pk_mul_f32 v[6:7], v[10:11], v[6:7]
	v_rcp_f32_e32 v9, v9
	v_cvt_pk_f16_f32 v10, v6, v7
	v_pack_b32_f16 v11, v4, v10
	v_cvt_f32_f16_sdwa v4, v133 dst_sel:DWORD dst_unused:UNUSED_PAD src0_sel:WORD_1
	v_rcp_f32_e32 v5, v5
	v_mov_b32_e32 v6, v61
	v_mov_b32_e32 v7, v62
	v_rcp_f32_e32 v4, v4
	v_pk_mul_f32 v[6:7], v[6:7], v[8:9]
	v_cvt_f32_f16_sdwa v9, v135 dst_sel:DWORD dst_unused:UNUSED_PAD src0_sel:WORD_1
	v_cvt_pk_f16_f32 v8, v6, v7
	v_pk_mov_b32 v[6:7], v[50:51], v[60:61] op_sel:[1,0]
	s_nop 0
	v_pk_mul_f32 v[4:5], v[6:7], v[4:5]
	s_nop 0
	v_cvt_pk_f16_f32 v4, v4, v5
	v_rcp_f32_e32 v5, v9
	v_alignbit_b32 v6, v4, v10, 16
	v_alignbit_b32 v7, v8, v4, 16
	v_lshrrev_b32_e32 v8, 16, v8
	v_fma_mixhi_f16 v8, v63, v5, 0
	v_lshrrev_b32_e32 v5, 4, v6
	v_and_b32_e32 v5, 0x10001, v5
	v_add3_u32 v5, v6, v5, s21
	v_lshrrev_b32_e32 v6, 4, v7
	v_and_b32_e32 v6, 0x10001, v6
	v_cvt_f32_f16_e32 v10, v128
	v_add3_u32 v6, v7, v6, s21
	v_lshrrev_b32_e32 v7, 4, v8
	v_lshrrev_b32_e32 v4, 4, v11
	v_and_b32_e32 v7, 0x10001, v7
	v_and_b32_e32 v4, 0x10001, v4
	v_add3_u32 v7, v8, v7, s21
	v_lshl_add_u64 v[8:9], v[80:81], 0, s[10:11]
	s_mov_b32 s10, 0xb0000
	v_add3_u32 v4, v11, v4, s21
	v_rcp_f32_e32 v12, v10
	v_add_co_u32_e32 v10, vcc, s10, v80
	v_and_b32_e32 v4, 0xfff0fff0, v4
	v_and_b32_e32 v5, 0xfff0fff0, v5
	v_and_b32_e32 v6, 0xfff0fff0, v6
	v_and_b32_e32 v7, 0xfff0fff0, v7
	v_addc_co_u32_e32 v11, vcc, 0, v81, vcc
	global_store_dwordx4 v[10:11], v[4:7], off
	v_cvt_f32_f16_e32 v11, v129
	s_andn2_b64 vcc, exec, s[40:41]
	v_cvt_f32_f16_sdwa v6, v128 dst_sel:DWORD dst_unused:UNUSED_PAD src0_sel:WORD_1
	v_cvt_f32_f16_sdwa v7, v130 dst_sel:DWORD dst_unused:UNUSED_PAD src0_sel:WORD_1
	v_fma_mixlo_f16 v4, v32, v12, 0
	v_mov_b32_e32 v12, v33
	v_rcp_f32_e32 v6, v6
	v_rcp_f32_e32 v10, v7
	v_rcp_f32_e32 v7, v11
	v_cvt_f32_f16_e32 v11, v131
	v_cvt_f32_f16_e32 v5, v130
	v_pk_mul_f32 v[6:7], v[12:13], v[6:7]
	s_nop 0
	v_cvt_pk_f16_f32 v12, v6, v7
	v_pack_b32_f16 v13, v4, v12
	v_cvt_f32_f16_sdwa v4, v129 dst_sel:DWORD dst_unused:UNUSED_PAD src0_sel:WORD_1
	v_rcp_f32_e32 v11, v11
	v_rcp_f32_e32 v5, v5
	v_mov_b32_e32 v6, v45
	v_mov_b32_e32 v7, v46
	v_rcp_f32_e32 v4, v4
	v_pk_mul_f32 v[6:7], v[6:7], v[10:11]
	v_cvt_f32_f16_sdwa v11, v131 dst_sel:DWORD dst_unused:UNUSED_PAD src0_sel:WORD_1
	v_cvt_pk_f16_f32 v10, v6, v7
	v_pk_mov_b32 v[6:7], v[34:35], v[44:45] op_sel:[1,0]
	s_nop 0
	v_pk_mul_f32 v[4:5], v[6:7], v[4:5]
	s_nop 0
	v_cvt_pk_f16_f32 v4, v4, v5
	v_rcp_f32_e32 v5, v11
	v_alignbit_b32 v6, v4, v12, 16
	v_alignbit_b32 v7, v10, v4, 16
	v_lshrrev_b32_e32 v10, 16, v10
	v_fma_mixhi_f16 v10, v47, v5, 0
	v_lshrrev_b32_e32 v5, 4, v6
	v_and_b32_e32 v5, 0x10001, v5
	v_add3_u32 v5, v6, v5, s21
	v_lshrrev_b32_e32 v6, 4, v7
	v_and_b32_e32 v6, 0x10001, v6
	v_lshrrev_b32_e32 v4, 4, v13
	v_add3_u32 v6, v7, v6, s21
	v_lshrrev_b32_e32 v7, 4, v10
	v_and_b32_e32 v4, 0x10001, v4
	v_and_b32_e32 v7, 0x10001, v7
	v_add3_u32 v4, v13, v4, s21
	v_add3_u32 v7, v10, v7, s21
	v_and_b32_e32 v4, 0xfff0fff0, v4
	v_and_b32_e32 v5, 0xfff0fff0, v5
	v_and_b32_e32 v6, 0xfff0fff0, v6
	v_and_b32_e32 v7, 0xfff0fff0, v7
	global_store_dwordx4 v[8:9], v[4:7], off offset:256
	s_cbranch_vccnz .LBB0_1739
	s_waitcnt vmcnt(0)
	v_readlane_b32 s4, v251, 63
	s_cmpk_gt_u32 s4, 0xff
	s_cbranch_scc1 .LBB0_1750
	s_barrier
